# v13 + P6 LN1 epilogue: the 16 serialized residual loads batched 8 at a time (2 round trips instead of 16)
# baseline (speedup 1.0000x reference)
; __device__ __forceinline__ float h2f_(unsigned short b) { return (float)__builtin_bit_cast(_Float16, b); }
;     __device__ __forceinline__ void fused(Acc& acc, const Unit& u, int wr, int wc, int fr, int fq, LAS unsigned char* lds, int wid, int lane) const {
;     ...
;             for (int m = 0; m < 4; ++m) { const size_t off = (size_t)(u.pm * BM + ai * HALF + wr * 64 + m * 16 + fr) * 1024 + col0;
; #pragma unroll
;                 for (int bj = 0; bj < 2; ++bj) { const size_t o = off + bj * HALF; const u32x4 bw = *(const u32x4*)(xb + o);
;                     f32x4 v0 = (f32x4){h2f_((unsigned short)(bw.x & 0xffffu)), h2f_((unsigned short)(bw.x >> 16)), h2f_((unsigned short)(bw.y & 0xffffu)), h2f_((unsigned short)(bw.y >> 16))} * ALPHA + acc[ai][bj][m][0] * sc;
;                     f32x4 v1 = (f32x4){h2f_((unsigned short)(bw.z & 0xffffu)), h2f_((unsigned short)(bw.z >> 16)), h2f_((unsigned short)(bw.w & 0xffffu)), h2f_((unsigned short)(bw.w >> 16))} * ALPHA + acc[ai][bj][m][1] * sc;
;                     if (add) { const u32x4 av = *(const u32x4*)(add + o);
;                         v0[0] += __uint_as_float(av.x << 16); v0[1] += __uint_as_float(av.x & 0xffff0000u); v0[2] += __uint_as_float(av.y << 16); v0[3] += __uint_as_float(av.y & 0xffff0000u);
;                         v1[0] += __uint_as_float(av.z << 16); v1[1] += __uint_as_float(av.z & 0xffff0000u); v1[2] += __uint_as_float(av.w << 16); v1[3] += __uint_as_float(av.w & 0xffff0000u); }
;                     acc[ai][bj][m][0] = v0; acc[ai][bj][m][1] = v1; }
.LBB0_1440:
	s_andn2_b64 vcc, exec, s[70:71]
	s_barrier
	v_mov_b32 v44, 0
	s_cbranch_vccnz .LBB0_1482
	s_add_u32 s8, s10, 0x1d600000
	v_add_u32_e32 v141, v44, v141
	s_addc_u32 s9, s11, 0
	s_lshl_b32 s0, s15, 5
	s_lshl_b32 s1, s6, 8
	s_lshl_b32 s2, s14, 8
	v_add_u32_e32 v197, s55, v141
	v_lshrrev_b32_e32 v45, 1, v140
	s_or_b32 s0, s1, s0
	v_add_u32_e32 v136, s2, v197
	v_and_or_b32 v152, v45, 24, s0
	v_ashrrev_i32_e32 v137, 31, v136
	v_ashrrev_i32_e32 v153, 31, v152
	v_lshlrev_b64 v[154:155], 10, v[136:137]
	v_lshl_add_u64 v[148:149], v[154:155], 0, v[152:153]
	v_lshl_add_u64 v[166:167], v[148:149], 1, s[8:9]
	global_load_dwordx4 v[142:145], v[166:167], off
	global_load_dwordx4 v[208:211], v[166:167], off offset:256
	s_mov_b64 s[98:99], 0x8000
	v_lshl_add_u64 v[146:147], v[166:167], 0, s[98:99]
	global_load_dwordx4 v[212:215], v[146:147], off
	global_load_dwordx4 v[216:219], v[146:147], off offset:256
	s_mov_b64 s[98:99], 0x10000
	v_lshl_add_u64 v[146:147], v[166:167], 0, s[98:99]
	global_load_dwordx4 v[220:223], v[146:147], off
	global_load_dwordx4 v[242:245], v[146:147], off offset:256
	s_mov_b64 s[98:99], 0x18000
	v_lshl_add_u64 v[146:147], v[166:167], 0, s[98:99]
	global_load_dwordx4 v[246:249], v[146:147], off
	global_load_dwordx4 v[250:253], v[146:147], off offset:256
	s_mov_b32 s0, 0x3fd744fd
	v_add_u32_e32 v150, 16, v136
	v_ashrrev_i32_e32 v151, 31, v150
	v_add_u32_e32 v176, 32, v136
	v_ashrrev_i32_e32 v177, 31, v176
	v_add_u32_e32 v180, 48, v136
	v_ashrrev_i32_e32 v181, 31, v180
	v_add_u32_e32 v184, 0x80, v136
	v_ashrrev_i32_e32 v185, 31, v184
	v_add_u32_e32 v188, 0x90, v136
	v_ashrrev_i32_e32 v189, 31, v188
	v_add_u32_e32 v192, 0xa0, v136
	v_ashrrev_i32_e32 v193, 31, v192
	v_add_u32_e32 v206, 0xb0, v136
	v_ashrrev_i32_e32 v207, 31, v206
	v_and_b32_e32 v34, 63, v140
	s_waitcnt vmcnt(0)
	v_cvt_f32_f16_e32 v44, v142
	v_cvt_f32_f16_sdwa v45, v142 dst_sel:DWORD dst_unused:UNUSED_PAD src0_sel:WORD_1
	v_cvt_f32_f16_e32 v46, v143
	v_cvt_f32_f16_sdwa v47, v143 dst_sel:DWORD dst_unused:UNUSED_PAD src0_sel:WORD_1
	v_pk_fma_f32 v[44:45], v[44:45], s[0:1], v[30:31] op_sel_hi:[1,0,1]
	v_cvt_f32_f16_e32 v30, v144
	v_pk_fma_f32 v[46:47], v[46:47], s[0:1], v[32:33] op_sel_hi:[1,0,1]
	v_cvt_f32_f16_sdwa v31, v144 dst_sel:DWORD dst_unused:UNUSED_PAD src0_sel:WORD_1
	v_cvt_f32_f16_e32 v32, v145
	v_cvt_f32_f16_sdwa v33, v145 dst_sel:DWORD dst_unused:UNUSED_PAD src0_sel:WORD_1
	v_pk_fma_f32 v[48:49], v[30:31], s[0:1], v[48:49] op_sel_hi:[1,0,1]
	v_pk_fma_f32 v[50:51], v[32:33], s[0:1], v[50:51] op_sel_hi:[1,0,1]
	v_cvt_f32_f16_e32 v138, v208
	v_cvt_f32_f16_sdwa v139, v208 dst_sel:DWORD dst_unused:UNUSED_PAD src0_sel:WORD_1
	v_cvt_f32_f16_e32 v30, v209
	v_cvt_f32_f16_sdwa v31, v209 dst_sel:DWORD dst_unused:UNUSED_PAD src0_sel:WORD_1
	v_pk_fma_f32 v[6:7], v[138:139], s[0:1], v[6:7] op_sel_hi:[1,0,1]
	v_lshlrev_b64 v[138:139], 1, v[152:153]
	v_pk_fma_f32 v[8:9], v[30:31], s[0:1], v[8:9] op_sel_hi:[1,0,1]
	v_cvt_f32_f16_e32 v30, v210
	v_cvt_f32_f16_sdwa v31, v210 dst_sel:DWORD dst_unused:UNUSED_PAD src0_sel:WORD_1
	v_cvt_f32_f16_e32 v32, v211
	v_cvt_f32_f16_sdwa v33, v211 dst_sel:DWORD dst_unused:UNUSED_PAD src0_sel:WORD_1
	v_pk_fma_f32 v[2:3], v[30:31], s[0:1], v[2:3] op_sel_hi:[1,0,1]
	v_lshlrev_b64 v[30:31], 11, v[150:151]
	v_lshl_add_u64 v[156:157], s[8:9], 0, v[30:31]
	v_pk_fma_f32 v[4:5], v[32:33], s[0:1], v[4:5] op_sel_hi:[1,0,1]
	v_lshl_add_u64 v[172:173], v[156:157], 0, v[138:139]
	v_cvt_f32_f16_e32 v142, v212
	v_cvt_f32_f16_sdwa v143, v212 dst_sel:DWORD dst_unused:UNUSED_PAD src0_sel:WORD_1
	v_cvt_f32_f16_e32 v30, v213
	v_cvt_f32_f16_sdwa v31, v213 dst_sel:DWORD dst_unused:UNUSED_PAD src0_sel:WORD_1
	v_pk_fma_f32 v[68:69], v[142:143], s[0:1], v[68:69] op_sel_hi:[1,0,1]
	v_pk_fma_f32 v[70:71], v[30:31], s[0:1], v[70:71] op_sel_hi:[1,0,1]
	v_cvt_f32_f16_e32 v30, v214
	v_cvt_f32_f16_sdwa v31, v214 dst_sel:DWORD dst_unused:UNUSED_PAD src0_sel:WORD_1
	v_cvt_f32_f16_e32 v32, v215
	v_cvt_f32_f16_sdwa v33, v215 dst_sel:DWORD dst_unused:UNUSED_PAD src0_sel:WORD_1
	v_pk_fma_f32 v[72:73], v[30:31], s[0:1], v[72:73] op_sel_hi:[1,0,1]
	v_pk_fma_f32 v[74:75], v[32:33], s[0:1], v[74:75] op_sel_hi:[1,0,1]
	v_cvt_f32_f16_e32 v142, v216
	v_cvt_f32_f16_sdwa v143, v216 dst_sel:DWORD dst_unused:UNUSED_PAD src0_sel:WORD_1
	v_cvt_f32_f16_e32 v30, v217
	v_cvt_f32_f16_sdwa v31, v217 dst_sel:DWORD dst_unused:UNUSED_PAD src0_sel:WORD_1
	v_pk_fma_f32 v[14:15], v[142:143], s[0:1], v[14:15] op_sel_hi:[1,0,1]
	v_pk_fma_f32 v[16:17], v[30:31], s[0:1], v[16:17] op_sel_hi:[1,0,1]
	v_cvt_f32_f16_e32 v30, v218
	v_cvt_f32_f16_sdwa v31, v218 dst_sel:DWORD dst_unused:UNUSED_PAD src0_sel:WORD_1
	v_cvt_f32_f16_e32 v32, v219
	v_cvt_f32_f16_sdwa v33, v219 dst_sel:DWORD dst_unused:UNUSED_PAD src0_sel:WORD_1
	v_pk_fma_f32 v[10:11], v[30:31], s[0:1], v[10:11] op_sel_hi:[1,0,1]
	v_lshlrev_b64 v[30:31], 11, v[176:177]
	v_pk_fma_f32 v[12:13], v[32:33], s[0:1], v[12:13] op_sel_hi:[1,0,1]
	v_lshl_add_u64 v[158:159], s[8:9], 0, v[30:31]
	v_lshl_add_u64 v[170:171], v[158:159], 0, v[138:139]
	v_cvt_f32_f16_e32 v142, v220
	v_cvt_f32_f16_sdwa v143, v220 dst_sel:DWORD dst_unused:UNUSED_PAD src0_sel:WORD_1
	v_cvt_f32_f16_e32 v30, v221
	v_cvt_f32_f16_sdwa v31, v221 dst_sel:DWORD dst_unused:UNUSED_PAD src0_sel:WORD_1
	v_pk_fma_f32 v[80:81], v[142:143], s[0:1], v[80:81] op_sel_hi:[1,0,1]
	v_pk_fma_f32 v[82:83], v[30:31], s[0:1], v[82:83] op_sel_hi:[1,0,1]
	v_cvt_f32_f16_e32 v30, v222
	v_cvt_f32_f16_sdwa v31, v222 dst_sel:DWORD dst_unused:UNUSED_PAD src0_sel:WORD_1
	v_cvt_f32_f16_e32 v32, v223
	v_cvt_f32_f16_sdwa v33, v223 dst_sel:DWORD dst_unused:UNUSED_PAD src0_sel:WORD_1
; __device__ __forceinline__ float h2f_(unsigned short b) { return (float)__builtin_bit_cast(_Float16, b); }
;     __device__ __forceinline__ void fused(Acc& acc, const Unit& u, int wr, int wc, int fr, int fq, LAS unsigned char* lds, int wid, int lane) const {
;     ...
;             for (int m = 0; m < 4; ++m) { const size_t off = (size_t)(u.pm * BM + ai * HALF + wr * 64 + m * 16 + fr) * 1024 + col0;
; #pragma unroll
;                 for (int bj = 0; bj < 2; ++bj) { const size_t o = off + bj * HALF; const u32x4 bw = *(const u32x4*)(xb + o);
;                     f32x4 v0 = (f32x4){h2f_((unsigned short)(bw.x & 0xffffu)), h2f_((unsigned short)(bw.x >> 16)), h2f_((unsigned short)(bw.y & 0xffffu)), h2f_((unsigned short)(bw.y >> 16))} * ALPHA + acc[ai][bj][m][0] * sc;
;                     f32x4 v1 = (f32x4){h2f_((unsigned short)(bw.z & 0xffffu)), h2f_((unsigned short)(bw.z >> 16)), h2f_((unsigned short)(bw.w & 0xffffu)), h2f_((unsigned short)(bw.w >> 16))} * ALPHA + acc[ai][bj][m][1] * sc;
;                     if (add) { const u32x4 av = *(const u32x4*)(add + o);
;                         v0[0] += __uint_as_float(av.x << 16); v0[1] += __uint_as_float(av.x & 0xffff0000u); v0[2] += __uint_as_float(av.y << 16); v0[3] += __uint_as_float(av.y & 0xffff0000u);
;                         v1[0] += __uint_as_float(av.z << 16); v1[1] += __uint_as_float(av.z & 0xffff0000u); v1[2] += __uint_as_float(av.w << 16); v1[3] += __uint_as_float(av.w & 0xffff0000u); }
;                     acc[ai][bj][m][0] = v0; acc[ai][bj][m][1] = v1; }
	v_pk_fma_f32 v[76:77], v[30:31], s[0:1], v[76:77] op_sel_hi:[1,0,1]
	v_pk_fma_f32 v[78:79], v[32:33], s[0:1], v[78:79] op_sel_hi:[1,0,1]
	v_cvt_f32_f16_e32 v142, v242
	v_cvt_f32_f16_sdwa v143, v242 dst_sel:DWORD dst_unused:UNUSED_PAD src0_sel:WORD_1
	v_cvt_f32_f16_e32 v30, v243
	v_cvt_f32_f16_sdwa v31, v243 dst_sel:DWORD dst_unused:UNUSED_PAD src0_sel:WORD_1
	v_pk_fma_f32 v[22:23], v[142:143], s[0:1], v[22:23] op_sel_hi:[1,0,1]
	v_pk_fma_f32 v[24:25], v[30:31], s[0:1], v[24:25] op_sel_hi:[1,0,1]
	v_cvt_f32_f16_e32 v30, v244
	v_cvt_f32_f16_sdwa v31, v244 dst_sel:DWORD dst_unused:UNUSED_PAD src0_sel:WORD_1
	v_cvt_f32_f16_e32 v32, v245
	v_cvt_f32_f16_sdwa v33, v245 dst_sel:DWORD dst_unused:UNUSED_PAD src0_sel:WORD_1
	v_pk_fma_f32 v[18:19], v[30:31], s[0:1], v[18:19] op_sel_hi:[1,0,1]
	v_lshlrev_b64 v[30:31], 11, v[180:181]
	v_lshl_add_u64 v[160:161], s[8:9], 0, v[30:31]
	v_pk_fma_f32 v[20:21], v[32:33], s[0:1], v[20:21] op_sel_hi:[1,0,1]
	v_lshl_add_u64 v[178:179], v[160:161], 0, v[138:139]
	v_cvt_f32_f16_e32 v142, v246
	v_cvt_f32_f16_sdwa v143, v246 dst_sel:DWORD dst_unused:UNUSED_PAD src0_sel:WORD_1
	v_cvt_f32_f16_e32 v30, v247
	v_cvt_f32_f16_sdwa v31, v247 dst_sel:DWORD dst_unused:UNUSED_PAD src0_sel:WORD_1
	v_pk_fma_f32 v[96:97], v[142:143], s[0:1], v[96:97] op_sel_hi:[1,0,1]
	v_pk_fma_f32 v[98:99], v[30:31], s[0:1], v[98:99] op_sel_hi:[1,0,1]
	v_cvt_f32_f16_e32 v30, v248
	v_cvt_f32_f16_sdwa v31, v248 dst_sel:DWORD dst_unused:UNUSED_PAD src0_sel:WORD_1
	v_cvt_f32_f16_e32 v32, v249
	v_cvt_f32_f16_sdwa v33, v249 dst_sel:DWORD dst_unused:UNUSED_PAD src0_sel:WORD_1
	v_pk_fma_f32 v[92:93], v[30:31], s[0:1], v[92:93] op_sel_hi:[1,0,1]
	v_pk_fma_f32 v[94:95], v[32:33], s[0:1], v[94:95] op_sel_hi:[1,0,1]
	v_cvt_f32_f16_e32 v30, v250
	v_cvt_f32_f16_sdwa v31, v250 dst_sel:DWORD dst_unused:UNUSED_PAD src0_sel:WORD_1
	v_cvt_f32_f16_e32 v32, v251
	v_cvt_f32_f16_sdwa v33, v251 dst_sel:DWORD dst_unused:UNUSED_PAD src0_sel:WORD_1
	v_pk_fma_f32 v[30:31], v[30:31], s[0:1], v[132:133] op_sel_hi:[1,0,1]
	v_cvt_f32_f16_e32 v132, v252
	v_cvt_f32_f16_sdwa v133, v252 dst_sel:DWORD dst_unused:UNUSED_PAD src0_sel:WORD_1
	v_pk_fma_f32 v[32:33], v[32:33], s[0:1], v[134:135] op_sel_hi:[1,0,1]
	v_cvt_f32_f16_e32 v134, v253
	v_cvt_f32_f16_sdwa v135, v253 dst_sel:DWORD dst_unused:UNUSED_PAD src0_sel:WORD_1
	v_pk_fma_f32 v[26:27], v[132:133], s[0:1], v[26:27] op_sel_hi:[1,0,1]
	v_lshlrev_b64 v[132:133], 11, v[184:185]
	v_lshl_add_u64 v[162:163], s[8:9], 0, v[132:133]
	v_pk_fma_f32 v[28:29], v[134:135], s[0:1], v[28:29] op_sel_hi:[1,0,1]
	v_lshl_add_u64 v[182:183], v[162:163], 0, v[138:139]
	global_load_dwordx4 v[132:135], v[182:183], off
	s_mov_b64 s[98:99], 0x40000
	v_lshl_add_u64 v[146:147], v[166:167], 0, s[98:99]
	global_load_dwordx4 v[208:211], v[146:147], off offset:256
	s_mov_b64 s[98:99], 0x48000
	v_lshl_add_u64 v[146:147], v[166:167], 0, s[98:99]
	global_load_dwordx4 v[212:215], v[146:147], off
	global_load_dwordx4 v[216:219], v[146:147], off offset:256
	s_mov_b64 s[98:99], 0x50000
	v_lshl_add_u64 v[146:147], v[166:167], 0, s[98:99]
	global_load_dwordx4 v[220:223], v[146:147], off
	global_load_dwordx4 v[242:245], v[146:147], off offset:256
	s_mov_b64 s[98:99], 0x58000
	v_lshl_add_u64 v[146:147], v[166:167], 0, s[98:99]
	global_load_dwordx4 v[246:249], v[146:147], off
	global_load_dwordx4 v[250:253], v[146:147], off offset:256
	s_waitcnt vmcnt(0)
	v_cvt_f32_f16_e32 v142, v132
	v_cvt_f32_f16_sdwa v143, v132 dst_sel:DWORD dst_unused:UNUSED_PAD src0_sel:WORD_1
	v_cvt_f32_f16_e32 v132, v133
	v_cvt_f32_f16_sdwa v133, v133 dst_sel:DWORD dst_unused:UNUSED_PAD src0_sel:WORD_1
	v_pk_fma_f32 v[104:105], v[142:143], s[0:1], v[104:105] op_sel_hi:[1,0,1]
	v_pk_fma_f32 v[106:107], v[132:133], s[0:1], v[106:107] op_sel_hi:[1,0,1]
	v_cvt_f32_f16_e32 v132, v134
	v_cvt_f32_f16_sdwa v133, v134 dst_sel:DWORD dst_unused:UNUSED_PAD src0_sel:WORD_1
	v_cvt_f32_f16_e32 v134, v135
	v_cvt_f32_f16_sdwa v135, v135 dst_sel:DWORD dst_unused:UNUSED_PAD src0_sel:WORD_1
	v_pk_fma_f32 v[100:101], v[132:133], s[0:1], v[100:101] op_sel_hi:[1,0,1]
	v_pk_fma_f32 v[102:103], v[134:135], s[0:1], v[102:103] op_sel_hi:[1,0,1]
	v_cvt_f32_f16_e32 v142, v208
	v_cvt_f32_f16_sdwa v143, v208 dst_sel:DWORD dst_unused:UNUSED_PAD src0_sel:WORD_1
	v_cvt_f32_f16_e32 v132, v209
	v_cvt_f32_f16_sdwa v133, v209 dst_sel:DWORD dst_unused:UNUSED_PAD src0_sel:WORD_1
	v_pk_fma_f32 v[40:41], v[142:143], s[0:1], v[40:41] op_sel_hi:[1,0,1]
	v_pk_fma_f32 v[42:43], v[132:133], s[0:1], v[42:43] op_sel_hi:[1,0,1]
	v_cvt_f32_f16_e32 v132, v210
	v_cvt_f32_f16_sdwa v133, v210 dst_sel:DWORD dst_unused:UNUSED_PAD src0_sel:WORD_1
	v_cvt_f32_f16_e32 v134, v211
	v_cvt_f32_f16_sdwa v135, v211 dst_sel:DWORD dst_unused:UNUSED_PAD src0_sel:WORD_1
	v_pk_fma_f32 v[36:37], v[132:133], s[0:1], v[36:37] op_sel_hi:[1,0,1]
	v_lshlrev_b64 v[132:133], 11, v[188:189]
	v_lshl_add_u64 v[164:165], s[8:9], 0, v[132:133]
	v_pk_fma_f32 v[38:39], v[134:135], s[0:1], v[38:39] op_sel_hi:[1,0,1]
	v_lshl_add_u64 v[186:187], v[164:165], 0, v[138:139]
	v_cvt_f32_f16_e32 v142, v212
	v_cvt_f32_f16_sdwa v143, v212 dst_sel:DWORD dst_unused:UNUSED_PAD src0_sel:WORD_1
	v_cvt_f32_f16_e32 v132, v213
	v_cvt_f32_f16_sdwa v133, v213 dst_sel:DWORD dst_unused:UNUSED_PAD src0_sel:WORD_1
	v_pk_fma_f32 v[112:113], v[142:143], s[0:1], v[112:113] op_sel_hi:[1,0,1]
	v_pk_fma_f32 v[114:115], v[132:133], s[0:1], v[114:115] op_sel_hi:[1,0,1]
	v_cvt_f32_f16_e32 v132, v214
	v_cvt_f32_f16_sdwa v133, v214 dst_sel:DWORD dst_unused:UNUSED_PAD src0_sel:WORD_1
	v_cvt_f32_f16_e32 v134, v215
	v_cvt_f32_f16_sdwa v135, v215 dst_sel:DWORD dst_unused:UNUSED_PAD src0_sel:WORD_1
; __device__ __forceinline__ float h2f_(unsigned short b) { return (float)__builtin_bit_cast(_Float16, b); }
;     __device__ __forceinline__ bool run(const f32x4 (&v)[2][2][4][2], const Unit& u, int wr, int wc, int fr, int fq, LAS unsigned char* lds, int wid, int lane) const {
;     ...
;                 float s = 0.f;
; #pragma unroll
;                 for (int bj = 0; bj < 2; ++bj)
; #pragma unroll
;                     for (int n = 0; n < 2; ++n) { const f32x4 x = v[ai][bj][m][n]; s += (x[0] + x[1]) + (x[2] + x[3]); }
;                 s += __shfl_xor(s, 16); s += __shfl_xor(s, 32);
;     __device__ __forceinline__ void fused(Acc& acc, const Unit& u, int wr, int wc, int fr, int fq, LAS unsigned char* lds, int wid, int lane) const {
;     ...
;             for (int m = 0; m < 4; ++m) { const size_t off = (size_t)(u.pm * BM + ai * HALF + wr * 64 + m * 16 + fr) * 1024 + col0;
; #pragma unroll
;                 for (int bj = 0; bj < 2; ++bj) { const size_t o = off + bj * HALF; const u32x4 bw = *(const u32x4*)(xb + o);
;                     f32x4 v0 = (f32x4){h2f_((unsigned short)(bw.x & 0xffffu)), h2f_((unsigned short)(bw.x >> 16)), h2f_((unsigned short)(bw.y & 0xffffu)), h2f_((unsigned short)(bw.y >> 16))} * ALPHA + acc[ai][bj][m][0] * sc;
;                     f32x4 v1 = (f32x4){h2f_((unsigned short)(bw.z & 0xffffu)), h2f_((unsigned short)(bw.z >> 16)), h2f_((unsigned short)(bw.w & 0xffffu)), h2f_((unsigned short)(bw.w >> 16))} * ALPHA + acc[ai][bj][m][1] * sc;
;                     if (add) { const u32x4 av = *(const u32x4*)(add + o);
;                         v0[0] += __uint_as_float(av.x << 16); v0[1] += __uint_as_float(av.x & 0xffff0000u); v0[2] += __uint_as_float(av.y << 16); v0[3] += __uint_as_float(av.y & 0xffff0000u);
;                         v1[0] += __uint_as_float(av.z << 16); v1[1] += __uint_as_float(av.z & 0xffff0000u); v1[2] += __uint_as_float(av.w << 16); v1[3] += __uint_as_float(av.w & 0xffff0000u); }
;                     acc[ai][bj][m][0] = v0; acc[ai][bj][m][1] = v1; }
;                 asm volatile("" : "+v"(acc[ai][0][m][0]), "+v"(acc[ai][0][m][1]), "+v"(acc[ai][1][m][0]), "+v"(acc[ai][1][m][1]));
;                 if (m & 1) asm volatile("" ::: "memory"); }
	v_pk_fma_f32 v[108:109], v[132:133], s[0:1], v[108:109] op_sel_hi:[1,0,1]
	v_pk_fma_f32 v[110:111], v[134:135], s[0:1], v[110:111] op_sel_hi:[1,0,1]
	v_cvt_f32_f16_e32 v142, v216
	v_cvt_f32_f16_sdwa v143, v216 dst_sel:DWORD dst_unused:UNUSED_PAD src0_sel:WORD_1
	v_cvt_f32_f16_e32 v132, v217
	v_cvt_f32_f16_sdwa v133, v217 dst_sel:DWORD dst_unused:UNUSED_PAD src0_sel:WORD_1
	v_pk_fma_f32 v[56:57], v[142:143], s[0:1], v[56:57] op_sel_hi:[1,0,1]
	v_pk_fma_f32 v[58:59], v[132:133], s[0:1], v[58:59] op_sel_hi:[1,0,1]
	v_cvt_f32_f16_e32 v132, v218
	v_cvt_f32_f16_sdwa v133, v218 dst_sel:DWORD dst_unused:UNUSED_PAD src0_sel:WORD_1
	v_cvt_f32_f16_e32 v134, v219
	v_cvt_f32_f16_sdwa v135, v219 dst_sel:DWORD dst_unused:UNUSED_PAD src0_sel:WORD_1
	v_pk_fma_f32 v[52:53], v[132:133], s[0:1], v[52:53] op_sel_hi:[1,0,1]
	v_lshlrev_b64 v[132:133], 11, v[192:193]
	v_pk_fma_f32 v[54:55], v[134:135], s[0:1], v[54:55] op_sel_hi:[1,0,1]
	v_lshl_add_u64 v[168:169], s[8:9], 0, v[132:133]
	v_lshl_add_u64 v[190:191], v[168:169], 0, v[138:139]
	v_cvt_f32_f16_e32 v142, v220
	v_cvt_f32_f16_sdwa v143, v220 dst_sel:DWORD dst_unused:UNUSED_PAD src0_sel:WORD_1
	v_cvt_f32_f16_e32 v132, v221
	v_cvt_f32_f16_sdwa v133, v221 dst_sel:DWORD dst_unused:UNUSED_PAD src0_sel:WORD_1
	v_pk_fma_f32 v[124:125], v[142:143], s[0:1], v[124:125] op_sel_hi:[1,0,1]
	v_pk_fma_f32 v[126:127], v[132:133], s[0:1], v[126:127] op_sel_hi:[1,0,1]
	v_cvt_f32_f16_e32 v132, v222
	v_cvt_f32_f16_sdwa v133, v222 dst_sel:DWORD dst_unused:UNUSED_PAD src0_sel:WORD_1
	v_cvt_f32_f16_e32 v134, v223
	v_cvt_f32_f16_sdwa v135, v223 dst_sel:DWORD dst_unused:UNUSED_PAD src0_sel:WORD_1
	v_pk_fma_f32 v[116:117], v[132:133], s[0:1], v[116:117] op_sel_hi:[1,0,1]
	v_pk_fma_f32 v[118:119], v[134:135], s[0:1], v[118:119] op_sel_hi:[1,0,1]
	v_cvt_f32_f16_e32 v142, v242
	v_cvt_f32_f16_sdwa v143, v242 dst_sel:DWORD dst_unused:UNUSED_PAD src0_sel:WORD_1
	v_cvt_f32_f16_e32 v132, v243
	v_cvt_f32_f16_sdwa v133, v243 dst_sel:DWORD dst_unused:UNUSED_PAD src0_sel:WORD_1
	v_pk_fma_f32 v[88:89], v[142:143], s[0:1], v[88:89] op_sel_hi:[1,0,1]
	v_add_f32_e32 v143, v8, v9
	v_pk_fma_f32 v[90:91], v[132:133], s[0:1], v[90:91] op_sel_hi:[1,0,1]
	v_cvt_f32_f16_e32 v132, v244
	v_cvt_f32_f16_sdwa v133, v244 dst_sel:DWORD dst_unused:UNUSED_PAD src0_sel:WORD_1
	v_cvt_f32_f16_e32 v134, v245
	v_cvt_f32_f16_sdwa v135, v245 dst_sel:DWORD dst_unused:UNUSED_PAD src0_sel:WORD_1
	v_mov_b32_e32 v142, v3
	v_pk_fma_f32 v[84:85], v[132:133], s[0:1], v[84:85] op_sel_hi:[1,0,1]
	v_lshlrev_b64 v[132:133], 11, v[206:207]
	v_lshl_add_u64 v[174:175], s[8:9], 0, v[132:133]
	v_pk_fma_f32 v[86:87], v[134:135], s[0:1], v[86:87] op_sel_hi:[1,0,1]
	v_lshl_add_u64 v[194:195], v[174:175], 0, v[138:139]
	v_mov_b32_e32 v138, v48
	v_mov_b32_e32 v139, v51
	v_cvt_f32_f16_e32 v136, v246
	v_cvt_f32_f16_sdwa v137, v246 dst_sel:DWORD dst_unused:UNUSED_PAD src0_sel:WORD_1
	v_cvt_f32_f16_e32 v132, v247
	v_cvt_f32_f16_sdwa v133, v247 dst_sel:DWORD dst_unused:UNUSED_PAD src0_sel:WORD_1
	v_pk_fma_f32 v[128:129], v[136:137], s[0:1], v[128:129] op_sel_hi:[1,0,1]
	v_pk_fma_f32 v[130:131], v[132:133], s[0:1], v[130:131] op_sel_hi:[1,0,1]
	v_cvt_f32_f16_e32 v132, v248
	v_cvt_f32_f16_sdwa v133, v248 dst_sel:DWORD dst_unused:UNUSED_PAD src0_sel:WORD_1
	v_cvt_f32_f16_e32 v134, v249
	v_cvt_f32_f16_sdwa v135, v249 dst_sel:DWORD dst_unused:UNUSED_PAD src0_sel:WORD_1
	v_pk_fma_f32 v[120:121], v[132:133], s[0:1], v[120:121] op_sel_hi:[1,0,1]
	v_pk_fma_f32 v[122:123], v[134:135], s[0:1], v[122:123] op_sel_hi:[1,0,1]
	v_cvt_f32_f16_e32 v136, v250
	v_cvt_f32_f16_sdwa v137, v250 dst_sel:DWORD dst_unused:UNUSED_PAD src0_sel:WORD_1
	v_cvt_f32_f16_e32 v132, v251
	v_cvt_f32_f16_sdwa v133, v251 dst_sel:DWORD dst_unused:UNUSED_PAD src0_sel:WORD_1
	v_pk_fma_f32 v[64:65], v[136:137], s[0:1], v[64:65] op_sel_hi:[1,0,1]
	v_mov_b32_e32 v136, v44
	v_pk_fma_f32 v[66:67], v[132:133], s[0:1], v[66:67] op_sel_hi:[1,0,1]
	v_cvt_f32_f16_e32 v132, v252
	v_cvt_f32_f16_sdwa v133, v252 dst_sel:DWORD dst_unused:UNUSED_PAD src0_sel:WORD_1
	v_cvt_f32_f16_e32 v134, v253
	v_cvt_f32_f16_sdwa v135, v253 dst_sel:DWORD dst_unused:UNUSED_PAD src0_sel:WORD_1
	v_mov_b32_e32 v137, v47
	v_pk_fma_f32 v[60:61], v[132:133], s[0:1], v[60:61] op_sel_hi:[1,0,1]
	v_and_b32_e32 v133, 64, v234
	v_xor_b32_e32 v132, 16, v234
	v_add_u32_e32 v133, 64, v133
	v_pk_fma_f32 v[62:63], v[134:135], s[0:1], v[62:63] op_sel_hi:[1,0,1]
	v_cmp_lt_i32_e32 vcc, v132, v133
	v_xor_b32_e32 v134, 32, v234
	v_mov_b32_e32 v135, v46
	v_cndmask_b32_e32 v132, v234, v132, vcc
	v_cmp_lt_i32_e32 vcc, v134, v133
	v_lshlrev_b32_e32 v132, 2, v132
	s_lshl_b32 s0, s15, 3
	v_cndmask_b32_e32 v133, v234, v134, vcc
	v_mov_b32_e32 v134, v45
	v_pk_add_f32 v[134:135], v[134:135], v[136:137]
	v_mov_b32_e32 v136, v49
	v_mov_b32_e32 v137, v50
	v_pk_add_f32 v[136:137], v[136:137], v[138:139]
	v_add_f32_e32 v134, v134, v135
	v_pk_add_f32 v[136:137], v[136:137], v[136:137] op_sel_hi:[0,1]
	v_add_f32_e32 v135, 0, v134
	v_add_f32_e32 v139, v6, v7
	v_mov_b32_e32 v138, v2
	v_mov_b32_e32 v136, v4
	v_mov_b32_e32 v134, v5
	v_pk_add_f32 v[138:139], v[138:139], v[142:143]
	v_pk_add_f32 v[134:135], v[136:137], v[134:135]
	v_lshlrev_b32_e32 v133, 2, v133
	v_pk_add_f32 v[134:135], v[138:139], v[134:135]
	v_cmp_gt_u32_e32 vcc, 16, v34
	v_add_f32_e32 v134, v134, v135
	ds_bpermute_b32 v135, v132, v134
	s_add_i32 s3, s33, s0
	s_waitcnt lgkmcnt(0)
;     __device__ __forceinline__ bool run(const f32x4 (&v)[2][2][4][2], const Unit& u, int wr, int wc, int fr, int fq, LAS unsigned char* lds, int wid, int lane) const {
;     ...
;                 float s = 0.f;
; #pragma unroll
;                 for (int bj = 0; bj < 2; ++bj)
; #pragma unroll
;                     for (int n = 0; n < 2; ++n) { const f32x4 x = v[ai][bj][m][n]; s += (x[0] + x[1]) + (x[2] + x[3]); }
;                 s += __shfl_xor(s, 16); s += __shfl_xor(s, 32);
;                 const float mw = s * (1.0f / 64.0f); float q = 0.f;
; #pragma unroll
;                 for (int bj = 0; bj < 2; ++bj)
; #pragma unroll
;                     for (int n = 0; n < 2; ++n) { const f32x4 d = v[ai][bj][m][n] - mw; q += (d[0] * d[0] + d[1] * d[1]) + (d[2] * d[2] + d[3] * d[3]); }
;                 q += __shfl_xor(q, 16); q += __shfl_xor(q, 32);
;                 if (fq == 0) P[(ai * HALF + wr * 64 + m * 16 + fr) * 4 + wc] = (f32x2){mw, q};
	v_add_f32_e32 v134, v134, v135
	ds_bpermute_b32 v135, v133, v134
	s_waitcnt lgkmcnt(0)
	v_add_f32_e32 v134, v134, v135
	v_fmamk_f32 v136, v134, 0xbc800000, v47
	v_fmamk_f32 v138, v134, 0xbc800000, v45
	v_fmamk_f32 v135, v134, 0xbc800000, v46
	v_fmamk_f32 v137, v134, 0xbc800000, v44
	v_mul_f32_e32 v138, v138, v138
	v_mul_f32_e32 v136, v136, v136
	v_fmac_f32_e32 v138, v137, v137
	v_fmac_f32_e32 v136, v135, v135
	v_fmamk_f32 v137, v134, 0xbc800000, v51
	v_fmamk_f32 v139, v134, 0xbc800000, v49
	v_add_f32_e32 v135, v138, v136
	v_fmamk_f32 v136, v134, 0xbc800000, v50
	v_fmamk_f32 v138, v134, 0xbc800000, v48
	v_mul_f32_e32 v139, v139, v139
	v_mul_f32_e32 v137, v137, v137
	v_fmac_f32_e32 v139, v138, v138
	v_fmac_f32_e32 v137, v136, v136
	v_add_f32_e32 v136, v139, v137
	v_fmamk_f32 v137, v134, 0xbc800000, v9
	v_fmamk_f32 v139, v134, 0xbc800000, v7
	v_add_f32_e32 v135, v135, v136
	v_fmamk_f32 v136, v134, 0xbc800000, v8
	v_fmamk_f32 v138, v134, 0xbc800000, v6
	v_mul_f32_e32 v139, v139, v139
	v_mul_f32_e32 v137, v137, v137
	v_fmac_f32_e32 v139, v138, v138
	v_fmac_f32_e32 v137, v136, v136
	v_add_f32_e32 v136, v139, v137
	v_fmamk_f32 v137, v134, 0xbc800000, v5
	v_fmamk_f32 v139, v134, 0xbc800000, v3
	v_add_f32_e32 v135, v136, v135
	v_fmamk_f32 v136, v134, 0xbc800000, v4
	v_fmamk_f32 v138, v134, 0xbc800000, v2
	v_mul_f32_e32 v139, v139, v139
	v_mul_f32_e32 v137, v137, v137
	v_fmac_f32_e32 v139, v138, v138
	v_fmac_f32_e32 v137, v136, v136
	v_add_f32_e32 v136, v139, v137
	v_add_f32_e32 v135, v136, v135
	ds_bpermute_b32 v136, v132, v135
	s_waitcnt lgkmcnt(0)
	v_add_f32_e32 v135, v135, v136
	ds_bpermute_b32 v136, v133, v135
	s_and_saveexec_b64 s[0:1], vcc
	s_cbranch_execz .LBB0_1443
	s_lshl_b32 s4, s13, 11
	s_add_i32 s4, s3, s4
	v_mul_f32_e32 v134, 0x3c800000, v134
	v_lshl_add_u32 v137, v141, 5, s4
	s_waitcnt lgkmcnt(0)
	v_add_f32_e32 v135, v135, v136
	ds_write_b64 v137, v[134:135]
